# v34 + nt cache policy on the norm phases' streaming output stores (bf16 GEMM-input rows and the context rows of the residual stream)
# baseline (speedup 1.0000x reference)
; #define LAS __attribute__((address_space(3)))
; __device__ __forceinline__ f32x4 h4_to_f32x4(u32x2 v) { return __builtin_convertvector(__builtin_bit_cast(f16x4, v), f32x4); }
; template <bool COMBINE, bool SRC_F32>
; __device__ __forceinline__ void norm_phase(LAS unsigned char* lds, const void* src_lat, const void* src_ctx, _Float16* xw_ctx, const float* part, int nrows, const float* g, const float* modl, int shift_idx, int scale_idx, bf16* HN, int tid, int lane, int wave) {
;     ...
;     for (int row = gw; row < nrows; row += NGW) {
;         if (row + NGW < nrows) NORM_LOAD(nv, row + NGW);
;         const int r = row < M_LAT ? (row >> 11) : 8;
;         float ss = 0.f;
; #pragma unroll
;         for (int j = 0; j < 8; ++j) ss += (v[j][0] * v[j][0] + v[j][1] * v[j][1]) + (v[j][2] * v[j][2] + v[j][3] * v[j][3]);
;         const float rstd = 1.0f / sqrtf(wave_sum_dpp(ss) * (1.0f / D) + EPS);
;         bf16* o = HN + (size_t)row * D;
;         f32x4 y[8];
; #pragma unroll
;         for (int j = 0; j < 8; ++j) { const int c = NORM_COL(j); y[j] = (v[j] * rstd) * h4_to_f32x4(*(const LAS u32x2*)(Gs + r * D + c)) + h4_to_f32x4(*(const LAS u32x2*)(Ss + r * D + c)); }
.LBB0_151:
	s_waitcnt vmcnt(7)
	v_mul_f32_e32 v68, v3, v3
	v_mul_f32_e32 v78, v5, v5
	v_fmac_f32_e32 v68, v2, v2
	v_fmac_f32_e32 v78, v4, v4
	v_add_f32_e32 v68, v68, v78
	s_waitcnt vmcnt(6)
	v_mul_f32_e32 v78, v63, v63
	v_mul_f32_e32 v79, v65, v65
	v_fmac_f32_e32 v78, v62, v62
	v_fmac_f32_e32 v79, v64, v64
	v_add_f32_e32 v78, v78, v79
	v_add_f32_e32 v68, v68, v78
	s_waitcnt vmcnt(5)
	v_mul_f32_e32 v78, v59, v59
	v_mul_f32_e32 v79, v61, v61
	v_fmac_f32_e32 v78, v58, v58
	v_fmac_f32_e32 v79, v60, v60
	v_add_f32_e32 v78, v78, v79
	v_add_f32_e32 v68, v78, v68
	s_waitcnt vmcnt(4)
	v_mul_f32_e32 v78, v55, v55
	v_mul_f32_e32 v79, v57, v57
	v_fmac_f32_e32 v78, v54, v54
	v_fmac_f32_e32 v79, v56, v56
	v_add_f32_e32 v78, v78, v79
	v_add_f32_e32 v68, v78, v68
	s_waitcnt vmcnt(3)
	v_mul_f32_e32 v78, v43, v43
	v_mul_f32_e32 v79, v45, v45
	v_fmac_f32_e32 v78, v42, v42
	v_fmac_f32_e32 v79, v44, v44
	v_add_f32_e32 v78, v78, v79
	v_add_f32_e32 v68, v78, v68
	s_waitcnt vmcnt(2)
	v_mul_f32_e32 v78, v31, v31
	v_mul_f32_e32 v79, v33, v33
	v_fmac_f32_e32 v78, v30, v30
	v_fmac_f32_e32 v79, v32, v32
	v_add_f32_e32 v78, v78, v79
	v_add_f32_e32 v68, v78, v68
	s_waitcnt vmcnt(1)
	v_mul_f32_e32 v78, v15, v15
	v_mul_f32_e32 v79, v17, v17
	v_fmac_f32_e32 v78, v14, v14
	v_fmac_f32_e32 v79, v16, v16
	v_add_f32_e32 v78, v78, v79
	v_add_f32_e32 v68, v78, v68
	s_waitcnt vmcnt(0)
	v_mul_f32_e32 v78, v7, v7
	v_mul_f32_e32 v79, v9, v9
	v_fmac_f32_e32 v78, v6, v6
	v_fmac_f32_e32 v79, v8, v8
	v_add_f32_e32 v78, v78, v79
	v_add_f32_e32 v68, v78, v68
	v_mov_b32_e32 v78, 0
	s_nop 0
	v_add_f32_dpp v68, v68, v68 quad_perm:[1,0,3,2] row_mask:0xf bank_mask:0xf bound_ctrl:1
	s_nop 1
	v_add_f32_dpp v68, v68, v68 quad_perm:[2,3,0,1] row_mask:0xf bank_mask:0xf bound_ctrl:1
	s_nop 1
	v_add_f32_dpp v68, v68, v68 row_half_mirror row_mask:0xf bank_mask:0xf bound_ctrl:1
	s_nop 1
	v_add_f32_dpp v68, v68, v68 row_mirror row_mask:0xf bank_mask:0xf bound_ctrl:1
	s_nop 1
	v_mov_b32_dpp v78, v68 row_bcast:15 row_mask:0xa bank_mask:0xf
	v_add_f32_e32 v68, v68, v78
	v_mov_b32_e32 v78, 0
	s_nop 1
	v_mov_b32_dpp v78, v68 row_bcast:31 row_mask:0xc bank_mask:0xf
	v_add_f32_e32 v68, v68, v78
	s_nop 0
	v_readlane_b32 s6, v68, 63
	s_nop 1
	v_fma_f32 v68, s6, v77, v75
	v_mul_f32_e32 v78, 0x4f800000, v68
	v_cmp_gt_f32_e32 vcc, s5, v68
	s_nop 1
	v_cndmask_b32_e32 v68, v68, v78, vcc
	v_sqrt_f32_e32 v78, v68
	s_nop 0
	v_add_u32_e32 v79, -1, v78
	v_fma_f32 v80, -v79, v78, v68
	v_cmp_ge_f32_e64 s[6:7], 0, v80
	v_add_u32_e32 v80, 1, v78
	s_nop 0
	v_cndmask_b32_e64 v79, v78, v79, s[6:7]
	v_fma_f32 v78, -v80, v78, v68
	v_cmp_lt_f32_e64 s[6:7], 0, v78
	s_nop 1
	v_cndmask_b32_e64 v78, v79, v80, s[6:7]
	v_mul_f32_e32 v79, 0x37800000, v78
	v_cndmask_b32_e32 v78, v78, v79, vcc
	v_cmp_class_f32_e32 vcc, v68, v76
	s_nop 1
	v_cndmask_b32_e32 v68, v78, v68, vcc
	v_div_scale_f32 v78, s[6:7], v68, v68, 1.0
	v_rcp_f32_e32 v82, v78
	s_min_i32 s6, s10, 0x4000
	s_and_b32 s6, s6, 0x7ffff800
	v_lshl_add_u32 v100, s6, 1, v69
	v_fma_f32 v79, -v78, v82, 1.0
	v_fmac_f32_e32 v82, v79, v82
	v_div_scale_f32 v79, vcc, 1.0, v68, 1.0
	v_mul_f32_e32 v83, v79, v82
	v_fma_f32 v80, -v78, v83, v79
	v_fmac_f32_e32 v83, v80, v82
	v_fma_f32 v84, -v78, v83, v79
	ds_read2st64_b64 v[78:81], v100 offset1:1
	ds_read2st64_b64 v[86:89], v100 offset0:72 offset1:73
	ds_read2st64_b64 v[90:93], v100 offset0:74 offset1:75
	v_div_fmas_f32 v82, v84, v82, v83
	v_div_fixup_f32 v68, v82, v68, 1.0
	ds_read2st64_b64 v[82:85], v100 offset0:2 offset1:3
	s_waitcnt lgkmcnt(3)
	v_cvt_f32_f16_e32 v94, v78
	v_cvt_f32_f16_sdwa v95, v78 dst_sel:DWORD dst_unused:UNUSED_PAD src0_sel:WORD_1
	v_cvt_f32_f16_e32 v78, v79
	v_cvt_f32_f16_sdwa v79, v79 dst_sel:DWORD dst_unused:UNUSED_PAD src0_sel:WORD_1
	s_waitcnt lgkmcnt(2)
	v_cvt_f32_f16_e32 v96, v86
	v_cvt_f32_f16_e32 v98, v87
	v_cvt_f32_f16_sdwa v99, v87 dst_sel:DWORD dst_unused:UNUSED_PAD src0_sel:WORD_1
	v_cvt_f32_f16_sdwa v97, v86 dst_sel:DWORD dst_unused:UNUSED_PAD src0_sel:WORD_1
	v_pk_mul_f32 v[2:3], v[2:3], v[68:69] op_sel_hi:[1,0]
	v_pk_mul_f32 v[4:5], v[4:5], v[68:69] op_sel_hi:[1,0]
	v_pk_mul_f32 v[62:63], v[62:63], v[68:69] op_sel_hi:[1,0]
	v_pk_fma_f32 v[78:79], v[4:5], v[78:79], v[98:99]
	v_pk_fma_f32 v[86:87], v[2:3], v[94:95], v[96:97]
	v_cvt_f32_f16_e32 v2, v80
	v_cvt_f32_f16_sdwa v3, v80 dst_sel:DWORD dst_unused:UNUSED_PAD src0_sel:WORD_1
	v_cvt_f32_f16_e32 v4, v81
	v_cvt_f32_f16_sdwa v5, v81 dst_sel:DWORD dst_unused:UNUSED_PAD src0_sel:WORD_1
	v_cvt_f32_f16_e32 v80, v88
	v_cvt_f32_f16_e32 v94, v89
	v_cvt_f32_f16_sdwa v95, v89 dst_sel:DWORD dst_unused:UNUSED_PAD src0_sel:WORD_1
	v_cvt_f32_f16_sdwa v81, v88 dst_sel:DWORD dst_unused:UNUSED_PAD src0_sel:WORD_1
	v_pk_mul_f32 v[64:65], v[64:65], v[68:69] op_sel_hi:[1,0]
	v_pk_mul_f32 v[58:59], v[58:59], v[68:69] op_sel_hi:[1,0]
	v_pk_fma_f32 v[88:89], v[64:65], v[4:5], v[94:95]
	v_pk_fma_f32 v[80:81], v[62:63], v[2:3], v[80:81]
	s_waitcnt lgkmcnt(0)
; __device__ __forceinline__ unsigned cvt_pk_bf16(float lo, float hi) { unsigned r; asm volatile("v_cvt_pk_bf16_f32 %0, %1, %2" : "=v"(r) : "v"(lo), "v"(hi)); return r; }
; #define LAS __attribute__((address_space(3)))
; __device__ __forceinline__ u32x2 f32x4_to_h4(f32x4 v) { return __builtin_bit_cast(u32x2, __builtin_convertvector(v, f16x4)); }
; __device__ __forceinline__ f32x4 h4_to_f32x4(u32x2 v) { return __builtin_convertvector(__builtin_bit_cast(f16x4, v), f32x4); }
; template <bool COMBINE, bool SRC_F32>
; __device__ __forceinline__ void norm_phase(LAS unsigned char* lds, const void* src_lat, const void* src_ctx, _Float16* xw_ctx, const float* part, int nrows, const float* g, const float* modl, int shift_idx, int scale_idx, bf16* HN, int tid, int lane, int wave) {
;     ...
;         for (int j = 0; j < 8; ++j) { const int c = NORM_COL(j); y[j] = (v[j] * rstd) * h4_to_f32x4(*(const LAS u32x2*)(Gs + r * D + c)) + h4_to_f32x4(*(const LAS u32x2*)(Ss + r * D + c)); }
;         if constexpr (SRC_F32) {
; #pragma unroll
;             for (int j = 0; j < 8; ++j) { u32x2 w; w.x = pg8::cvt_pk_bf16(y[j][0], y[j][1]); w.y = pg8::cvt_pk_bf16(y[j][2], y[j][3]); *(u32x2*)(o + NORM_COL(j)) = w; }
;         } else {
; #pragma unroll
;             for (int j = 0; j < 4; ++j) { u32x4 w; w.x = pg8::cvt_pk_bf16(y[2 * j][0], y[2 * j][1]); w.y = pg8::cvt_pk_bf16(y[2 * j][2], y[2 * j][3]); w.z = pg8::cvt_pk_bf16(y[2 * j + 1][0], y[2 * j + 1][1]); w.w = pg8::cvt_pk_bf16(y[2 * j + 1][2], y[2 * j + 1][3]);
;                 *(u32x4*)(o + NORM_COL(2 * j)) = w; }
;         }
;         if (COMBINE && row >= M_LAT) {
; #pragma unroll
;             for (int j = 0; j < 4; ++j) { const u32x2 h0 = f32x4_to_h4(v[2 * j]), h1 = f32x4_to_h4(v[2 * j + 1]); *(u32x4*)(xw_ctx + (size_t)(row - M_LAT) * D + NORM_COL(2 * j)) = (u32x4){h0.x, h0.y, h1.x, h1.y}; }
;         }
; #pragma unroll
;         for (int j = 0; j < 8; ++j) v[j] = nv[j];
	v_cvt_f32_f16_e32 v2, v82
	v_cvt_f32_f16_sdwa v3, v82 dst_sel:DWORD dst_unused:UNUSED_PAD src0_sel:WORD_1
	v_cvt_f32_f16_e32 v4, v83
	v_cvt_f32_f16_sdwa v5, v83 dst_sel:DWORD dst_unused:UNUSED_PAD src0_sel:WORD_1
	v_cvt_f32_f16_e32 v62, v90
	v_cvt_f32_f16_e32 v64, v91
	v_cvt_f32_f16_sdwa v65, v91 dst_sel:DWORD dst_unused:UNUSED_PAD src0_sel:WORD_1
	v_cvt_f32_f16_sdwa v63, v90 dst_sel:DWORD dst_unused:UNUSED_PAD src0_sel:WORD_1
	v_pk_mul_f32 v[60:61], v[60:61], v[68:69] op_sel_hi:[1,0]
	v_pk_mul_f32 v[54:55], v[54:55], v[68:69] op_sel_hi:[1,0]
	v_pk_fma_f32 v[82:83], v[60:61], v[4:5], v[64:65]
	v_pk_fma_f32 v[90:91], v[58:59], v[2:3], v[62:63]
	v_cvt_f32_f16_e32 v58, v84
	v_cvt_f32_f16_sdwa v59, v84 dst_sel:DWORD dst_unused:UNUSED_PAD src0_sel:WORD_1
	v_cvt_f32_f16_e32 v60, v85
	v_cvt_f32_f16_sdwa v61, v85 dst_sel:DWORD dst_unused:UNUSED_PAD src0_sel:WORD_1
	v_cvt_f32_f16_e32 v62, v92
	v_cvt_f32_f16_e32 v64, v93
	v_cvt_f32_f16_sdwa v65, v93 dst_sel:DWORD dst_unused:UNUSED_PAD src0_sel:WORD_1
	v_cvt_f32_f16_sdwa v63, v92 dst_sel:DWORD dst_unused:UNUSED_PAD src0_sel:WORD_1
	v_pk_mul_f32 v[56:57], v[56:57], v[68:69] op_sel_hi:[1,0]
	ds_read2st64_b64 v[2:5], v100 offset0:4 offset1:5
	v_pk_fma_f32 v[84:85], v[56:57], v[60:61], v[64:65]
	v_pk_fma_f32 v[92:93], v[54:55], v[58:59], v[62:63]
	ds_read2st64_b64 v[58:61], v100 offset0:76 offset1:77
	ds_read2st64_b64 v[62:65], v100 offset0:78 offset1:79
	ds_read2st64_b64 v[54:57], v100 offset0:6 offset1:7
	s_waitcnt lgkmcnt(3)
	v_cvt_f32_f16_e32 v94, v2
	v_cvt_f32_f16_sdwa v95, v2 dst_sel:DWORD dst_unused:UNUSED_PAD src0_sel:WORD_1
	v_cvt_f32_f16_e32 v2, v3
	v_cvt_f32_f16_sdwa v3, v3 dst_sel:DWORD dst_unused:UNUSED_PAD src0_sel:WORD_1
	s_waitcnt lgkmcnt(2)
	v_cvt_f32_f16_e32 v96, v58
	v_cvt_f32_f16_e32 v98, v59
	v_cvt_f32_f16_sdwa v99, v59 dst_sel:DWORD dst_unused:UNUSED_PAD src0_sel:WORD_1
	v_cvt_f32_f16_sdwa v97, v58 dst_sel:DWORD dst_unused:UNUSED_PAD src0_sel:WORD_1
	v_pk_mul_f32 v[42:43], v[42:43], v[68:69] op_sel_hi:[1,0]
	v_pk_mul_f32 v[44:45], v[44:45], v[68:69] op_sel_hi:[1,0]
	v_cvt_f32_f16_e32 v58, v60
	v_pk_fma_f32 v[2:3], v[44:45], v[2:3], v[98:99]
	v_pk_fma_f32 v[42:43], v[42:43], v[94:95], v[96:97]
	v_cvt_f32_f16_e32 v44, v4
	v_cvt_f32_f16_sdwa v45, v4 dst_sel:DWORD dst_unused:UNUSED_PAD src0_sel:WORD_1
	v_cvt_f32_f16_e32 v4, v5
	v_cvt_f32_f16_sdwa v5, v5 dst_sel:DWORD dst_unused:UNUSED_PAD src0_sel:WORD_1
	v_cvt_f32_f16_e32 v94, v61
	v_cvt_f32_f16_sdwa v95, v61 dst_sel:DWORD dst_unused:UNUSED_PAD src0_sel:WORD_1
	v_cvt_f32_f16_sdwa v59, v60 dst_sel:DWORD dst_unused:UNUSED_PAD src0_sel:WORD_1
	v_pk_mul_f32 v[30:31], v[30:31], v[68:69] op_sel_hi:[1,0]
	v_pk_mul_f32 v[32:33], v[32:33], v[68:69] op_sel_hi:[1,0]
	v_pk_mul_f32 v[14:15], v[14:15], v[68:69] op_sel_hi:[1,0]
	v_pk_fma_f32 v[4:5], v[32:33], v[4:5], v[94:95]
	v_pk_fma_f32 v[30:31], v[30:31], v[44:45], v[58:59]
	s_waitcnt lgkmcnt(0)
	v_cvt_f32_f16_e32 v32, v54
	v_cvt_f32_f16_sdwa v33, v54 dst_sel:DWORD dst_unused:UNUSED_PAD src0_sel:WORD_1
	v_cvt_f32_f16_e32 v44, v55
	v_cvt_f32_f16_sdwa v45, v55 dst_sel:DWORD dst_unused:UNUSED_PAD src0_sel:WORD_1
	v_cvt_f32_f16_e32 v54, v62
	v_cvt_f32_f16_sdwa v55, v62 dst_sel:DWORD dst_unused:UNUSED_PAD src0_sel:WORD_1
	v_cvt_f32_f16_e32 v58, v63
	v_cvt_f32_f16_sdwa v59, v63 dst_sel:DWORD dst_unused:UNUSED_PAD src0_sel:WORD_1
	v_pk_mul_f32 v[6:7], v[6:7], v[68:69] op_sel_hi:[1,0]
	v_pk_fma_f32 v[14:15], v[14:15], v[32:33], v[54:55]
	v_cvt_f32_f16_e32 v32, v56
	v_cvt_f32_f16_sdwa v33, v56 dst_sel:DWORD dst_unused:UNUSED_PAD src0_sel:WORD_1
	v_cvt_f32_f16_e32 v54, v64
	v_cvt_f32_f16_sdwa v55, v64 dst_sel:DWORD dst_unused:UNUSED_PAD src0_sel:WORD_1
	v_pk_mul_f32 v[16:17], v[16:17], v[68:69] op_sel_hi:[1,0]
	v_cvt_f32_f16_e32 v56, v65
	v_pk_fma_f32 v[16:17], v[16:17], v[44:45], v[58:59]
	v_pk_fma_f32 v[6:7], v[6:7], v[32:33], v[54:55]
	v_cvt_pk_bf16_f32 v32, v86, v87
	v_cvt_pk_bf16_f32 v33, v78, v79
	global_store_dwordx2 v[66:67], v[32:33], off nt
	v_cvt_pk_bf16_f32 v32, v80, v81
	v_cvt_pk_bf16_f32 v33, v88, v89
	v_cvt_f32_f16_e32 v44, v57
	v_cvt_f32_f16_sdwa v45, v57 dst_sel:DWORD dst_unused:UNUSED_PAD src0_sel:WORD_1
	v_cvt_f32_f16_sdwa v57, v65 dst_sel:DWORD dst_unused:UNUSED_PAD src0_sel:WORD_1
	global_store_dwordx2 v[66:67], v[32:33], off offset:512 nt
	v_cvt_pk_bf16_f32 v32, v90, v91
	v_cvt_pk_bf16_f32 v33, v82, v83
	global_store_dwordx2 v[66:67], v[32:33], off offset:1024 nt
	v_cvt_pk_bf16_f32 v32, v92, v93
	v_cvt_pk_bf16_f32 v33, v84, v85
	global_store_dwordx2 v[66:67], v[32:33], off offset:1536 nt
	v_cvt_pk_bf16_f32 v32, v42, v43
	v_cvt_pk_bf16_f32 v33, v2, v3
	global_store_dwordx2 v[66:67], v[32:33], off offset:2048 nt
	v_cvt_pk_bf16_f32 v2, v30, v31
	v_cvt_pk_bf16_f32 v3, v4, v5
	v_pk_mul_f32 v[8:9], v[8:9], v[68:69] op_sel_hi:[1,0]
	global_store_dwordx2 v[66:67], v[2:3], off offset:2560 nt
	v_cvt_pk_bf16_f32 v2, v14, v15
	v_cvt_pk_bf16_f32 v3, v16, v17
	v_pk_fma_f32 v[8:9], v[8:9], v[44:45], v[56:57]
	global_store_dwordx2 v[66:67], v[2:3], off offset:3072 nt
	v_cvt_pk_bf16_f32 v2, v6, v7
	v_cvt_pk_bf16_f32 v3, v8, v9
	global_store_dwordx2 v[66:67], v[2:3], off offset:3584 nt
	v_lshl_add_u64 v[66:67], v[66:67], 0, s[8:9]
	s_andn2_b64 vcc, exec, s[12:13]
	s_mov_b32 s10, s11
	v_mov_b32_e32 v2, v10
	v_mov_b32_e32 v3, v11
	v_mov_b32_e32 v4, v12
	v_mov_b32_e32 v5, v13
	v_mov_b32_e32 v62, v18
	v_mov_b32_e32 v63, v19
	v_mov_b32_e32 v64, v20
	v_mov_b32_e32 v65, v21
	v_mov_b32_e32 v58, v22
	v_mov_b32_e32 v59, v23
	v_mov_b32_e32 v60, v24
	v_mov_b32_e32 v61, v25
	v_mov_b32_e32 v54, v26
	v_mov_b32_e32 v55, v27
	v_mov_b32_e32 v56, v28
	v_mov_b32_e32 v57, v29
	v_mov_b32_e32 v42, v34
	v_mov_b32_e32 v43, v35
	v_mov_b32_e32 v44, v36
	v_mov_b32_e32 v45, v37
	v_mov_b32_e32 v30, v38
	v_mov_b32_e32 v31, v39
	v_mov_b32_e32 v32, v40
	v_mov_b32_e32 v33, v41
	v_mov_b32_e32 v14, v46
	v_mov_b32_e32 v15, v47
	v_mov_b32_e32 v16, v48
	v_mov_b32_e32 v17, v49
	v_mov_b32_e32 v6, v50
	v_mov_b32_e32 v7, v51
	v_mov_b32_e32 v8, v52
	v_mov_b32_e32 v9, v53
	s_cbranch_vccz .LBB0_154

; #define LAS __attribute__((address_space(3)))
; __device__ __forceinline__ f32x4 h4_to_f32x4(u32x2 v) { return __builtin_convertvector(__builtin_bit_cast(f16x4, v), f32x4); }
; template <bool COMBINE, bool SRC_F32>
; __device__ __forceinline__ void norm_phase(LAS unsigned char* lds, const void* src_lat, const void* src_ctx, _Float16* xw_ctx, const float* part, int nrows, const float* g, const float* modl, int shift_idx, int scale_idx, bf16* HN, int tid, int lane, int wave) {
;     ...
;     for (int row = gw; row < nrows; row += NGW) {
;         if (row + NGW < nrows) NORM_LOAD(nv, row + NGW);
;         const int r = row < M_LAT ? (row >> 11) : 8;
;         float ss = 0.f;
; #pragma unroll
;         for (int j = 0; j < 8; ++j) ss += (v[j][0] * v[j][0] + v[j][1] * v[j][1]) + (v[j][2] * v[j][2] + v[j][3] * v[j][3]);
;         const float rstd = 1.0f / sqrtf(wave_sum_dpp(ss) * (1.0f / D) + EPS);
;         bf16* o = HN + (size_t)row * D;
;         f32x4 y[8];
; #pragma unroll
;         for (int j = 0; j < 8; ++j) { const int c = NORM_COL(j); y[j] = (v[j] * rstd) * h4_to_f32x4(*(const LAS u32x2*)(Gs + r * D + c)) + h4_to_f32x4(*(const LAS u32x2*)(Ss + r * D + c)); }
.LBB0_470:
	v_mul_f32_e32 v72, v35, v35
	v_mul_f32_e32 v79, v37, v37
	v_fmac_f32_e32 v72, v34, v34
	v_fmac_f32_e32 v79, v36, v36
	v_add_f32_e32 v72, v72, v79
	v_mul_f32_e32 v79, v39, v39
	v_mul_f32_e32 v80, v41, v41
	v_fmac_f32_e32 v79, v38, v38
	v_fmac_f32_e32 v80, v40, v40
	v_add_f32_e32 v79, v79, v80
	v_add_f32_e32 v72, v72, v79
	v_mul_f32_e32 v79, v43, v43
	v_mul_f32_e32 v80, v45, v45
	v_fmac_f32_e32 v79, v42, v42
	v_fmac_f32_e32 v80, v44, v44
	v_add_f32_e32 v79, v79, v80
	v_add_f32_e32 v72, v79, v72
	v_mul_f32_e32 v79, v47, v47
	v_mul_f32_e32 v80, v49, v49
	v_fmac_f32_e32 v79, v46, v46
	v_fmac_f32_e32 v80, v48, v48
	v_add_f32_e32 v79, v79, v80
	v_add_f32_e32 v72, v79, v72
	v_mul_f32_e32 v79, v51, v51
	v_mul_f32_e32 v80, v53, v53
	v_fmac_f32_e32 v79, v50, v50
	v_fmac_f32_e32 v80, v52, v52
	v_add_f32_e32 v79, v79, v80
	v_add_f32_e32 v72, v79, v72
	v_mul_f32_e32 v79, v55, v55
	v_mul_f32_e32 v80, v57, v57
	v_fmac_f32_e32 v79, v54, v54
	v_fmac_f32_e32 v80, v56, v56
	v_add_f32_e32 v79, v79, v80
	v_add_f32_e32 v72, v79, v72
	v_mul_f32_e32 v79, v59, v59
	v_mul_f32_e32 v80, v61, v61
	v_fmac_f32_e32 v79, v58, v58
	v_fmac_f32_e32 v80, v60, v60
	v_add_f32_e32 v79, v79, v80
	v_add_f32_e32 v72, v79, v72
	v_mul_f32_e32 v79, v63, v63
	v_mul_f32_e32 v80, v65, v65
	v_fmac_f32_e32 v79, v62, v62
	v_fmac_f32_e32 v80, v64, v64
	v_add_f32_e32 v79, v79, v80
	v_add_f32_e32 v72, v79, v72
	v_mov_b32_e32 v79, 0
	s_nop 0
	v_add_f32_dpp v72, v72, v72 quad_perm:[1,0,3,2] row_mask:0xf bank_mask:0xf bound_ctrl:1
	s_nop 1
	v_add_f32_dpp v72, v72, v72 quad_perm:[2,3,0,1] row_mask:0xf bank_mask:0xf bound_ctrl:1
	s_nop 1
	v_add_f32_dpp v72, v72, v72 row_half_mirror row_mask:0xf bank_mask:0xf bound_ctrl:1
	s_nop 1
	v_add_f32_dpp v72, v72, v72 row_mirror row_mask:0xf bank_mask:0xf bound_ctrl:1
	s_nop 1
	v_mov_b32_dpp v79, v72 row_bcast:15 row_mask:0xa bank_mask:0xf
	v_add_f32_e32 v72, v72, v79
	v_mov_b32_e32 v79, 0
	s_nop 1
	v_mov_b32_dpp v79, v72 row_bcast:31 row_mask:0xc bank_mask:0xf
	v_add_f32_e32 v72, v72, v79
	s_nop 0
	v_readlane_b32 s0, v72, 63
	s_nop 1
	v_fma_f32 v72, s0, v78, v76
	v_mul_f32_e32 v79, 0x4f800000, v72
	v_cmp_gt_f32_e32 vcc, s7, v72
	s_nop 1
	v_cndmask_b32_e32 v72, v72, v79, vcc
	v_sqrt_f32_e32 v79, v72
	s_nop 0
	v_add_u32_e32 v80, -1, v79
	v_fma_f32 v81, -v80, v79, v72
	v_cmp_ge_f32_e64 s[0:1], 0, v81
	v_add_u32_e32 v81, 1, v79
	s_nop 0
	v_cndmask_b32_e64 v80, v79, v80, s[0:1]
	v_fma_f32 v79, -v81, v79, v72
	v_cmp_lt_f32_e64 s[0:1], 0, v79
	s_nop 1
	v_cndmask_b32_e64 v79, v80, v81, s[0:1]
	v_mul_f32_e32 v80, 0x37800000, v79
	v_cndmask_b32_e32 v79, v79, v80, vcc
	v_cmp_class_f32_e32 vcc, v72, v77
	s_nop 1
	v_cndmask_b32_e32 v72, v79, v72, vcc
	v_div_scale_f32 v79, s[0:1], v72, v72, 1.0
	v_rcp_f32_e32 v84, v79
	s_add_i32 s0, s8, 0x4000
	s_min_i32 s1, s0, 0x4000
	s_and_b32 s1, s1, 0x7ffff800
	v_fma_f32 v80, -v79, v84, 1.0
	v_fmac_f32_e32 v84, v80, v84
	v_div_scale_f32 v80, vcc, 1.0, v72, 1.0
	v_mul_f32_e32 v85, v80, v84
	v_fma_f32 v81, -v79, v85, v80
	v_fmac_f32_e32 v85, v81, v84
	v_lshl_add_u32 v114, s1, 1, v67
	v_fma_f32 v79, -v79, v85, v80
	ds_read_b128 v[80:83], v114
	ds_read_b128 v[88:91], v114 offset:36864
	ds_read_b128 v[92:95], v114 offset:37888
	v_div_fmas_f32 v79, v79, v84, v85
	ds_read_b128 v[84:87], v114 offset:1024
	s_waitcnt lgkmcnt(3)
	v_cvt_f32_f16_e32 v96, v80
	v_cvt_f32_f16_sdwa v97, v80 dst_sel:DWORD dst_unused:UNUSED_PAD src0_sel:WORD_1
	v_cvt_f32_f16_e32 v80, v81
	v_cvt_f32_f16_sdwa v81, v81 dst_sel:DWORD dst_unused:UNUSED_PAD src0_sel:WORD_1
	s_waitcnt lgkmcnt(2)
	v_cvt_f32_f16_e32 v98, v88
	v_cvt_f32_f16_e32 v100, v89
	v_cvt_f32_f16_sdwa v101, v89 dst_sel:DWORD dst_unused:UNUSED_PAD src0_sel:WORD_1
	v_cvt_f32_f16_sdwa v99, v88 dst_sel:DWORD dst_unused:UNUSED_PAD src0_sel:WORD_1
	v_div_fixup_f32 v72, v79, v72, 1.0
	v_pk_mul_f32 v[88:89], v[34:35], v[72:73] op_sel_hi:[1,0]
	v_pk_mul_f32 v[102:103], v[36:37], v[72:73] op_sel_hi:[1,0]
	v_pk_fma_f32 v[96:97], v[88:89], v[96:97], v[98:99]
	v_pk_fma_f32 v[100:101], v[102:103], v[80:81], v[100:101]
	v_cvt_f32_f16_e32 v80, v82
	v_cvt_f32_f16_sdwa v81, v82 dst_sel:DWORD dst_unused:UNUSED_PAD src0_sel:WORD_1
	v_cvt_f32_f16_e32 v82, v83
	v_cvt_f32_f16_sdwa v83, v83 dst_sel:DWORD dst_unused:UNUSED_PAD src0_sel:WORD_1
	v_cvt_f32_f16_e32 v88, v90
	v_cvt_f32_f16_e32 v98, v91
	v_cvt_f32_f16_sdwa v99, v91 dst_sel:DWORD dst_unused:UNUSED_PAD src0_sel:WORD_1
	v_cvt_f32_f16_sdwa v89, v90 dst_sel:DWORD dst_unused:UNUSED_PAD src0_sel:WORD_1
	v_pk_mul_f32 v[90:91], v[38:39], v[72:73] op_sel_hi:[1,0]
	v_pk_mul_f32 v[102:103], v[40:41], v[72:73] op_sel_hi:[1,0]
	v_pk_mul_f32 v[118:119], v[52:53], v[72:73] op_sel_hi:[1,0]
	v_pk_fma_f32 v[98:99], v[102:103], v[82:83], v[98:99]
	v_pk_fma_f32 v[102:103], v[90:91], v[80:81], v[88:89]
	s_waitcnt lgkmcnt(0)
; __device__ __forceinline__ unsigned cvt_pk_bf16(float lo, float hi) { unsigned r; asm volatile("v_cvt_pk_bf16_f32 %0, %1, %2" : "=v"(r) : "v"(lo), "v"(hi)); return r; }
; #define LAS __attribute__((address_space(3)))
; __device__ __forceinline__ u32x2 f32x4_to_h4(f32x4 v) { return __builtin_bit_cast(u32x2, __builtin_convertvector(v, f16x4)); }
; __device__ __forceinline__ f32x4 h4_to_f32x4(u32x2 v) { return __builtin_convertvector(__builtin_bit_cast(f16x4, v), f32x4); }
; template <bool COMBINE, bool SRC_F32>
; __device__ __forceinline__ void norm_phase(LAS unsigned char* lds, const void* src_lat, const void* src_ctx, _Float16* xw_ctx, const float* part, int nrows, const float* g, const float* modl, int shift_idx, int scale_idx, bf16* HN, int tid, int lane, int wave) {
;     ...
;         for (int j = 0; j < 8; ++j) { const int c = NORM_COL(j); y[j] = (v[j] * rstd) * h4_to_f32x4(*(const LAS u32x2*)(Gs + r * D + c)) + h4_to_f32x4(*(const LAS u32x2*)(Ss + r * D + c)); }
;         if constexpr (SRC_F32) {
; #pragma unroll
;             for (int j = 0; j < 8; ++j) { u32x2 w; w.x = pg8::cvt_pk_bf16(y[j][0], y[j][1]); w.y = pg8::cvt_pk_bf16(y[j][2], y[j][3]); *(u32x2*)(o + NORM_COL(j)) = w; }
;         } else {
; #pragma unroll
;             for (int j = 0; j < 4; ++j) { u32x4 w; w.x = pg8::cvt_pk_bf16(y[2 * j][0], y[2 * j][1]); w.y = pg8::cvt_pk_bf16(y[2 * j][2], y[2 * j][3]); w.z = pg8::cvt_pk_bf16(y[2 * j + 1][0], y[2 * j + 1][1]); w.w = pg8::cvt_pk_bf16(y[2 * j + 1][2], y[2 * j + 1][3]);
;                 *(u32x4*)(o + NORM_COL(2 * j)) = w; }
;         }
;         if (COMBINE && row >= M_LAT) {
; #pragma unroll
;             for (int j = 0; j < 4; ++j) { const u32x2 h0 = f32x4_to_h4(v[2 * j]), h1 = f32x4_to_h4(v[2 * j + 1]); *(u32x4*)(xw_ctx + (size_t)(row - M_LAT) * D + NORM_COL(2 * j)) = (u32x4){h0.x, h0.y, h1.x, h1.y}; }
;         }
; #pragma unroll
;         for (int j = 0; j < 8; ++j) v[j] = nv[j];
	v_cvt_f32_f16_e32 v80, v84
	v_cvt_f32_f16_sdwa v81, v84 dst_sel:DWORD dst_unused:UNUSED_PAD src0_sel:WORD_1
	v_cvt_f32_f16_e32 v82, v85
	v_cvt_f32_f16_sdwa v83, v85 dst_sel:DWORD dst_unused:UNUSED_PAD src0_sel:WORD_1
	v_cvt_f32_f16_e32 v84, v92
	v_cvt_f32_f16_e32 v88, v93
	v_cvt_f32_f16_sdwa v89, v93 dst_sel:DWORD dst_unused:UNUSED_PAD src0_sel:WORD_1
	v_cvt_f32_f16_sdwa v85, v92 dst_sel:DWORD dst_unused:UNUSED_PAD src0_sel:WORD_1
	v_pk_mul_f32 v[90:91], v[42:43], v[72:73] op_sel_hi:[1,0]
	v_pk_mul_f32 v[92:93], v[44:45], v[72:73] op_sel_hi:[1,0]
	s_cmpk_lt_i32 s0, 0x4000
	v_pk_fma_f32 v[104:105], v[92:93], v[82:83], v[88:89]
	v_pk_fma_f32 v[106:107], v[90:91], v[80:81], v[84:85]
	v_cvt_f32_f16_e32 v88, v86
	v_cvt_f32_f16_sdwa v89, v86 dst_sel:DWORD dst_unused:UNUSED_PAD src0_sel:WORD_1
	v_cvt_f32_f16_e32 v90, v94
	v_cvt_f32_f16_sdwa v91, v94 dst_sel:DWORD dst_unused:UNUSED_PAD src0_sel:WORD_1
	v_pk_mul_f32 v[84:85], v[46:47], v[72:73] op_sel_hi:[1,0]
	ds_read_b128 v[80:83], v114 offset:2048
	v_cvt_f32_f16_e32 v86, v87
	v_pk_fma_f32 v[110:111], v[84:85], v[88:89], v[90:91]
	ds_read_b128 v[88:91], v114 offset:38912
	v_cvt_f32_f16_sdwa v87, v87 dst_sel:DWORD dst_unused:UNUSED_PAD src0_sel:WORD_1
	v_cvt_f32_f16_e32 v92, v95
	v_cvt_f32_f16_sdwa v93, v95 dst_sel:DWORD dst_unused:UNUSED_PAD src0_sel:WORD_1
	v_pk_mul_f32 v[94:95], v[48:49], v[72:73] op_sel_hi:[1,0]
	s_nop 0
	v_pk_fma_f32 v[108:109], v[94:95], v[86:87], v[92:93]
	ds_read_b128 v[84:87], v114 offset:3072
	s_waitcnt lgkmcnt(2)
	v_cvt_f32_f16_e32 v112, v80
	v_cvt_f32_f16_sdwa v113, v80 dst_sel:DWORD dst_unused:UNUSED_PAD src0_sel:WORD_1
	v_cvt_f32_f16_e32 v80, v81
	v_cvt_f32_f16_sdwa v81, v81 dst_sel:DWORD dst_unused:UNUSED_PAD src0_sel:WORD_1
	ds_read_b128 v[92:95], v114 offset:39936
	s_waitcnt lgkmcnt(2)
	v_cvt_f32_f16_e32 v114, v88
	v_cvt_f32_f16_e32 v116, v89
	v_cvt_f32_f16_sdwa v117, v89 dst_sel:DWORD dst_unused:UNUSED_PAD src0_sel:WORD_1
	v_cvt_f32_f16_sdwa v115, v88 dst_sel:DWORD dst_unused:UNUSED_PAD src0_sel:WORD_1
	v_pk_mul_f32 v[88:89], v[50:51], v[72:73] op_sel_hi:[1,0]
	v_pk_fma_f32 v[116:117], v[118:119], v[80:81], v[116:117]
	v_pk_fma_f32 v[88:89], v[88:89], v[112:113], v[114:115]
	v_cvt_f32_f16_e32 v80, v82
	v_cvt_f32_f16_sdwa v81, v82 dst_sel:DWORD dst_unused:UNUSED_PAD src0_sel:WORD_1
	v_cvt_f32_f16_e32 v82, v83
	v_cvt_f32_f16_sdwa v83, v83 dst_sel:DWORD dst_unused:UNUSED_PAD src0_sel:WORD_1
	v_cvt_f32_f16_e32 v112, v90
	v_cvt_f32_f16_e32 v114, v91
	v_cvt_f32_f16_sdwa v115, v91 dst_sel:DWORD dst_unused:UNUSED_PAD src0_sel:WORD_1
	v_cvt_f32_f16_sdwa v113, v90 dst_sel:DWORD dst_unused:UNUSED_PAD src0_sel:WORD_1
	v_pk_mul_f32 v[90:91], v[54:55], v[72:73] op_sel_hi:[1,0]
	v_pk_mul_f32 v[118:119], v[56:57], v[72:73] op_sel_hi:[1,0]
	v_pk_fma_f32 v[90:91], v[90:91], v[80:81], v[112:113]
	v_pk_fma_f32 v[114:115], v[118:119], v[82:83], v[114:115]
	s_waitcnt lgkmcnt(1)
	v_cvt_f32_f16_e32 v80, v84
	v_cvt_f32_f16_sdwa v81, v84 dst_sel:DWORD dst_unused:UNUSED_PAD src0_sel:WORD_1
	v_cvt_f32_f16_e32 v82, v85
	v_cvt_f32_f16_sdwa v83, v85 dst_sel:DWORD dst_unused:UNUSED_PAD src0_sel:WORD_1
	s_waitcnt lgkmcnt(0)
	v_cvt_f32_f16_e32 v84, v92
	v_cvt_f32_f16_e32 v112, v93
	v_cvt_f32_f16_sdwa v113, v93 dst_sel:DWORD dst_unused:UNUSED_PAD src0_sel:WORD_1
	v_cvt_f32_f16_sdwa v85, v92 dst_sel:DWORD dst_unused:UNUSED_PAD src0_sel:WORD_1
	v_pk_mul_f32 v[92:93], v[58:59], v[72:73] op_sel_hi:[1,0]
	v_pk_mul_f32 v[118:119], v[60:61], v[72:73] op_sel_hi:[1,0]
	v_pk_fma_f32 v[84:85], v[92:93], v[80:81], v[84:85]
	v_pk_fma_f32 v[112:113], v[118:119], v[82:83], v[112:113]
	v_cvt_f32_f16_e32 v80, v86
	v_cvt_f32_f16_sdwa v81, v86 dst_sel:DWORD dst_unused:UNUSED_PAD src0_sel:WORD_1
	v_cvt_f32_f16_e32 v82, v87
	v_cvt_f32_f16_sdwa v83, v87 dst_sel:DWORD dst_unused:UNUSED_PAD src0_sel:WORD_1
	v_cvt_f32_f16_e32 v86, v94
	v_cvt_f32_f16_e32 v92, v95
	v_cvt_f32_f16_sdwa v93, v95 dst_sel:DWORD dst_unused:UNUSED_PAD src0_sel:WORD_1
	v_cvt_f32_f16_sdwa v87, v94 dst_sel:DWORD dst_unused:UNUSED_PAD src0_sel:WORD_1
	v_pk_mul_f32 v[94:95], v[62:63], v[72:73] op_sel_hi:[1,0]
	v_pk_mul_f32 v[118:119], v[64:65], v[72:73] op_sel_hi:[1,0]
	v_pk_fma_f32 v[86:87], v[94:95], v[80:81], v[86:87]
	v_pk_fma_f32 v[92:93], v[118:119], v[82:83], v[92:93]
	v_cvt_pk_bf16_f32 v80, v96, v97
	v_cvt_pk_bf16_f32 v81, v100, v101
	v_cvt_pk_bf16_f32 v82, v102, v103
	v_cvt_pk_bf16_f32 v83, v98, v99
	global_store_dwordx4 v[70:71], v[80:83], off nt
	s_nop 1
	v_cvt_pk_bf16_f32 v80, v106, v107
	v_cvt_pk_bf16_f32 v81, v104, v105
	v_cvt_pk_bf16_f32 v82, v110, v111
	v_cvt_pk_bf16_f32 v83, v108, v109
	global_store_dwordx4 v[70:71], v[80:83], off offset:1024 nt
	s_nop 1
	v_cvt_pk_bf16_f32 v80, v88, v89
	v_cvt_pk_bf16_f32 v81, v116, v117
	v_cvt_pk_bf16_f32 v82, v90, v91
	v_cvt_pk_bf16_f32 v83, v114, v115
	global_store_dwordx4 v[70:71], v[80:83], off offset:2048 nt
	s_nop 1
	v_cvt_pk_bf16_f32 v80, v84, v85
	v_cvt_pk_bf16_f32 v81, v112, v113
	v_cvt_pk_bf16_f32 v82, v86, v87
	v_cvt_pk_bf16_f32 v83, v92, v93
	global_store_dwordx4 v[70:71], v[80:83], off offset:3072 nt
	s_cbranch_scc1 .LBB0_466
	s_lshl_b64 s[0:1], s[8:9], 12
	v_cvt_pk_f16_f32 v81, v36, v37
	v_cvt_pk_f16_f32 v80, v34, v35
	v_cvt_pk_f16_f32 v82, v38, v39
	v_lshl_add_u64 v[38:39], v[68:69], 0, s[0:1]
	v_cvt_pk_f16_f32 v35, v44, v45
	v_cvt_pk_f16_f32 v34, v42, v43
	v_cvt_pk_f16_f32 v37, v48, v49
	v_cvt_pk_f16_f32 v36, v46, v47
	global_store_dwordx4 v[38:39], v[34:37], off offset:1024 nt
	v_cvt_pk_f16_f32 v83, v40, v41
	global_store_dwordx4 v[38:39], v[80:83], off nt
	v_cvt_pk_f16_f32 v35, v52, v53
	v_cvt_pk_f16_f32 v34, v50, v51
	v_cvt_pk_f16_f32 v37, v56, v57
	v_cvt_pk_f16_f32 v36, v54, v55
	global_store_dwordx4 v[38:39], v[34:37], off offset:2048 nt
	s_nop 1
	v_cvt_pk_f16_f32 v35, v60, v61
	v_cvt_pk_f16_f32 v34, v58, v59
	v_cvt_pk_f16_f32 v37, v64, v65
	v_cvt_pk_f16_f32 v36, v62, v63
	global_store_dwordx4 v[38:39], v[34:37], off offset:3072 nt
	s_branch .LBB0_466

; #define LAS __attribute__((address_space(3)))
; __device__ __forceinline__ f32x4 h4_to_f32x4(u32x2 v) { return __builtin_convertvector(__builtin_bit_cast(f16x4, v), f32x4); }
; template <bool COMBINE, bool SRC_F32>
; __device__ __forceinline__ void norm_phase(LAS unsigned char* lds, const void* src_lat, const void* src_ctx, _Float16* xw_ctx, const float* part, int nrows, const float* g, const float* modl, int shift_idx, int scale_idx, bf16* HN, int tid, int lane, int wave) {
;     ...
;     for (int row = gw; row < nrows; row += NGW) {
;         if (row + NGW < nrows) NORM_LOAD(nv, row + NGW);
;         const int r = row < M_LAT ? (row >> 11) : 8;
;         float ss = 0.f;
; #pragma unroll
;         for (int j = 0; j < 8; ++j) ss += (v[j][0] * v[j][0] + v[j][1] * v[j][1]) + (v[j][2] * v[j][2] + v[j][3] * v[j][3]);
;         const float rstd = 1.0f / sqrtf(wave_sum_dpp(ss) * (1.0f / D) + EPS);
;         bf16* o = HN + (size_t)row * D;
;         f32x4 y[8];
; #pragma unroll
;         for (int j = 0; j < 8; ++j) { const int c = NORM_COL(j); y[j] = (v[j] * rstd) * h4_to_f32x4(*(const LAS u32x2*)(Gs + r * D + c)) + h4_to_f32x4(*(const LAS u32x2*)(Ss + r * D + c)); }
.LBB0_1381:
	v_mul_f32_e32 v72, v35, v35
	v_mul_f32_e32 v79, v37, v37
	v_fmac_f32_e32 v72, v34, v34
	v_fmac_f32_e32 v79, v36, v36
	v_add_f32_e32 v72, v72, v79
	v_mul_f32_e32 v79, v39, v39
	v_mul_f32_e32 v80, v41, v41
	v_fmac_f32_e32 v79, v38, v38
	v_fmac_f32_e32 v80, v40, v40
	v_add_f32_e32 v79, v79, v80
	v_add_f32_e32 v72, v72, v79
	v_mul_f32_e32 v79, v43, v43
	v_mul_f32_e32 v80, v45, v45
	v_fmac_f32_e32 v79, v42, v42
	v_fmac_f32_e32 v80, v44, v44
	v_add_f32_e32 v79, v79, v80
	v_add_f32_e32 v72, v79, v72
	v_mul_f32_e32 v79, v47, v47
	v_mul_f32_e32 v80, v49, v49
	v_fmac_f32_e32 v79, v46, v46
	v_fmac_f32_e32 v80, v48, v48
	v_add_f32_e32 v79, v79, v80
	v_add_f32_e32 v72, v79, v72
	v_mul_f32_e32 v79, v51, v51
	v_mul_f32_e32 v80, v53, v53
	v_fmac_f32_e32 v79, v50, v50
	v_fmac_f32_e32 v80, v52, v52
	v_add_f32_e32 v79, v79, v80
	v_add_f32_e32 v72, v79, v72
	v_mul_f32_e32 v79, v55, v55
	v_mul_f32_e32 v80, v57, v57
	v_fmac_f32_e32 v79, v54, v54
	v_fmac_f32_e32 v80, v56, v56
	v_add_f32_e32 v79, v79, v80
	v_add_f32_e32 v72, v79, v72
	v_mul_f32_e32 v79, v59, v59
	v_mul_f32_e32 v80, v61, v61
	v_fmac_f32_e32 v79, v58, v58
	v_fmac_f32_e32 v80, v60, v60
	v_add_f32_e32 v79, v79, v80
	v_add_f32_e32 v72, v79, v72
	v_mul_f32_e32 v79, v63, v63
	v_mul_f32_e32 v80, v65, v65
	v_fmac_f32_e32 v79, v62, v62
	v_fmac_f32_e32 v80, v64, v64
	v_add_f32_e32 v79, v79, v80
	v_add_f32_e32 v72, v79, v72
	v_mov_b32_e32 v79, 0
	s_nop 0
	v_add_f32_dpp v72, v72, v72 quad_perm:[1,0,3,2] row_mask:0xf bank_mask:0xf bound_ctrl:1
	s_nop 1
	v_add_f32_dpp v72, v72, v72 quad_perm:[2,3,0,1] row_mask:0xf bank_mask:0xf bound_ctrl:1
	s_nop 1
	v_add_f32_dpp v72, v72, v72 row_half_mirror row_mask:0xf bank_mask:0xf bound_ctrl:1
	s_nop 1
	v_add_f32_dpp v72, v72, v72 row_mirror row_mask:0xf bank_mask:0xf bound_ctrl:1
	s_nop 1
	v_mov_b32_dpp v79, v72 row_bcast:15 row_mask:0xa bank_mask:0xf
	v_add_f32_e32 v72, v72, v79
	v_mov_b32_e32 v79, 0
	s_nop 1
	v_mov_b32_dpp v79, v72 row_bcast:31 row_mask:0xc bank_mask:0xf
	v_add_f32_e32 v72, v72, v79
	s_nop 0
	v_readlane_b32 s0, v72, 63
	s_nop 1
	v_fma_f32 v72, s0, v78, v76
	v_mul_f32_e32 v79, 0x4f800000, v72
	v_cmp_gt_f32_e32 vcc, s5, v72
	s_nop 1
	v_cndmask_b32_e32 v72, v72, v79, vcc
	v_sqrt_f32_e32 v79, v72
	s_nop 0
	v_add_u32_e32 v80, -1, v79
	v_fma_f32 v81, -v80, v79, v72
	v_cmp_ge_f32_e64 s[0:1], 0, v81
	v_add_u32_e32 v81, 1, v79
	s_nop 0
	v_cndmask_b32_e64 v80, v79, v80, s[0:1]
	v_fma_f32 v79, -v81, v79, v72
	v_cmp_lt_f32_e64 s[0:1], 0, v79
	s_nop 1
	v_cndmask_b32_e64 v79, v80, v81, s[0:1]
	v_mul_f32_e32 v80, 0x37800000, v79
	v_cndmask_b32_e32 v79, v79, v80, vcc
	v_cmp_class_f32_e32 vcc, v72, v77
	s_nop 1
	v_cndmask_b32_e32 v72, v79, v72, vcc
	v_div_scale_f32 v79, s[0:1], v72, v72, 1.0
	v_rcp_f32_e32 v84, v79
	s_add_i32 s0, s8, 0x4000
	s_min_i32 s1, s0, 0x4000
	s_and_b32 s1, s1, 0x7ffff800
	v_fma_f32 v80, -v79, v84, 1.0
	v_fmac_f32_e32 v84, v80, v84
	v_div_scale_f32 v80, vcc, 1.0, v72, 1.0
	v_mul_f32_e32 v85, v80, v84
	v_fma_f32 v81, -v79, v85, v80
	v_fmac_f32_e32 v85, v81, v84
	v_lshl_add_u32 v114, s1, 1, v67
	v_fma_f32 v79, -v79, v85, v80
	ds_read_b128 v[80:83], v114
	ds_read_b128 v[88:91], v114 offset:36864
	ds_read_b128 v[92:95], v114 offset:37888
	v_div_fmas_f32 v79, v79, v84, v85
	ds_read_b128 v[84:87], v114 offset:1024
	s_waitcnt lgkmcnt(3)
	v_cvt_f32_f16_e32 v96, v80
	v_cvt_f32_f16_sdwa v97, v80 dst_sel:DWORD dst_unused:UNUSED_PAD src0_sel:WORD_1
	v_cvt_f32_f16_e32 v80, v81
	v_cvt_f32_f16_sdwa v81, v81 dst_sel:DWORD dst_unused:UNUSED_PAD src0_sel:WORD_1
	s_waitcnt lgkmcnt(2)
	v_cvt_f32_f16_e32 v98, v88
	v_cvt_f32_f16_e32 v100, v89
	v_cvt_f32_f16_sdwa v101, v89 dst_sel:DWORD dst_unused:UNUSED_PAD src0_sel:WORD_1
	v_cvt_f32_f16_sdwa v99, v88 dst_sel:DWORD dst_unused:UNUSED_PAD src0_sel:WORD_1
	v_div_fixup_f32 v72, v79, v72, 1.0
	v_pk_mul_f32 v[88:89], v[34:35], v[72:73] op_sel_hi:[1,0]
	v_pk_mul_f32 v[102:103], v[36:37], v[72:73] op_sel_hi:[1,0]
	v_pk_fma_f32 v[96:97], v[88:89], v[96:97], v[98:99]
	v_pk_fma_f32 v[100:101], v[102:103], v[80:81], v[100:101]
	v_cvt_f32_f16_e32 v80, v82
	v_cvt_f32_f16_sdwa v81, v82 dst_sel:DWORD dst_unused:UNUSED_PAD src0_sel:WORD_1
	v_cvt_f32_f16_e32 v82, v83
	v_cvt_f32_f16_sdwa v83, v83 dst_sel:DWORD dst_unused:UNUSED_PAD src0_sel:WORD_1
	v_cvt_f32_f16_e32 v88, v90
	v_cvt_f32_f16_e32 v98, v91
	v_cvt_f32_f16_sdwa v99, v91 dst_sel:DWORD dst_unused:UNUSED_PAD src0_sel:WORD_1
	v_cvt_f32_f16_sdwa v89, v90 dst_sel:DWORD dst_unused:UNUSED_PAD src0_sel:WORD_1
	v_pk_mul_f32 v[90:91], v[38:39], v[72:73] op_sel_hi:[1,0]
	v_pk_mul_f32 v[102:103], v[40:41], v[72:73] op_sel_hi:[1,0]
	v_pk_mul_f32 v[118:119], v[52:53], v[72:73] op_sel_hi:[1,0]
	v_pk_fma_f32 v[98:99], v[102:103], v[82:83], v[98:99]
	v_pk_fma_f32 v[102:103], v[90:91], v[80:81], v[88:89]
	s_waitcnt lgkmcnt(0)
; __device__ __forceinline__ unsigned cvt_pk_bf16(float lo, float hi) { unsigned r; asm volatile("v_cvt_pk_bf16_f32 %0, %1, %2" : "=v"(r) : "v"(lo), "v"(hi)); return r; }
; #define LAS __attribute__((address_space(3)))
; __device__ __forceinline__ u32x2 f32x4_to_h4(f32x4 v) { return __builtin_bit_cast(u32x2, __builtin_convertvector(v, f16x4)); }
; __device__ __forceinline__ f32x4 h4_to_f32x4(u32x2 v) { return __builtin_convertvector(__builtin_bit_cast(f16x4, v), f32x4); }
; template <bool COMBINE, bool SRC_F32>
; __device__ __forceinline__ void norm_phase(LAS unsigned char* lds, const void* src_lat, const void* src_ctx, _Float16* xw_ctx, const float* part, int nrows, const float* g, const float* modl, int shift_idx, int scale_idx, bf16* HN, int tid, int lane, int wave) {
;     ...
;         for (int j = 0; j < 8; ++j) { const int c = NORM_COL(j); y[j] = (v[j] * rstd) * h4_to_f32x4(*(const LAS u32x2*)(Gs + r * D + c)) + h4_to_f32x4(*(const LAS u32x2*)(Ss + r * D + c)); }
;         if constexpr (SRC_F32) {
; #pragma unroll
;             for (int j = 0; j < 8; ++j) { u32x2 w; w.x = pg8::cvt_pk_bf16(y[j][0], y[j][1]); w.y = pg8::cvt_pk_bf16(y[j][2], y[j][3]); *(u32x2*)(o + NORM_COL(j)) = w; }
;         } else {
; #pragma unroll
;             for (int j = 0; j < 4; ++j) { u32x4 w; w.x = pg8::cvt_pk_bf16(y[2 * j][0], y[2 * j][1]); w.y = pg8::cvt_pk_bf16(y[2 * j][2], y[2 * j][3]); w.z = pg8::cvt_pk_bf16(y[2 * j + 1][0], y[2 * j + 1][1]); w.w = pg8::cvt_pk_bf16(y[2 * j + 1][2], y[2 * j + 1][3]);
;                 *(u32x4*)(o + NORM_COL(2 * j)) = w; }
;         }
;         if (COMBINE && row >= M_LAT) {
; #pragma unroll
;             for (int j = 0; j < 4; ++j) { const u32x2 h0 = f32x4_to_h4(v[2 * j]), h1 = f32x4_to_h4(v[2 * j + 1]); *(u32x4*)(xw_ctx + (size_t)(row - M_LAT) * D + NORM_COL(2 * j)) = (u32x4){h0.x, h0.y, h1.x, h1.y}; }
;         }
; #pragma unroll
;         for (int j = 0; j < 8; ++j) v[j] = nv[j];
	v_cvt_f32_f16_e32 v80, v84
	v_cvt_f32_f16_sdwa v81, v84 dst_sel:DWORD dst_unused:UNUSED_PAD src0_sel:WORD_1
	v_cvt_f32_f16_e32 v82, v85
	v_cvt_f32_f16_sdwa v83, v85 dst_sel:DWORD dst_unused:UNUSED_PAD src0_sel:WORD_1
	v_cvt_f32_f16_e32 v84, v92
	v_cvt_f32_f16_e32 v88, v93
	v_cvt_f32_f16_sdwa v89, v93 dst_sel:DWORD dst_unused:UNUSED_PAD src0_sel:WORD_1
	v_cvt_f32_f16_sdwa v85, v92 dst_sel:DWORD dst_unused:UNUSED_PAD src0_sel:WORD_1
	v_pk_mul_f32 v[90:91], v[42:43], v[72:73] op_sel_hi:[1,0]
	v_pk_mul_f32 v[92:93], v[44:45], v[72:73] op_sel_hi:[1,0]
	s_cmpk_lt_i32 s0, 0x4000
	v_pk_fma_f32 v[104:105], v[92:93], v[82:83], v[88:89]
	v_pk_fma_f32 v[106:107], v[90:91], v[80:81], v[84:85]
	v_cvt_f32_f16_e32 v88, v86
	v_cvt_f32_f16_sdwa v89, v86 dst_sel:DWORD dst_unused:UNUSED_PAD src0_sel:WORD_1
	v_cvt_f32_f16_e32 v90, v94
	v_cvt_f32_f16_sdwa v91, v94 dst_sel:DWORD dst_unused:UNUSED_PAD src0_sel:WORD_1
	v_pk_mul_f32 v[84:85], v[46:47], v[72:73] op_sel_hi:[1,0]
	ds_read_b128 v[80:83], v114 offset:2048
	v_cvt_f32_f16_e32 v86, v87
	v_pk_fma_f32 v[110:111], v[84:85], v[88:89], v[90:91]
	ds_read_b128 v[88:91], v114 offset:38912
	v_cvt_f32_f16_sdwa v87, v87 dst_sel:DWORD dst_unused:UNUSED_PAD src0_sel:WORD_1
	v_cvt_f32_f16_e32 v92, v95
	v_cvt_f32_f16_sdwa v93, v95 dst_sel:DWORD dst_unused:UNUSED_PAD src0_sel:WORD_1
	v_pk_mul_f32 v[94:95], v[48:49], v[72:73] op_sel_hi:[1,0]
	s_nop 0
	v_pk_fma_f32 v[108:109], v[94:95], v[86:87], v[92:93]
	ds_read_b128 v[84:87], v114 offset:3072
	s_waitcnt lgkmcnt(2)
	v_cvt_f32_f16_e32 v112, v80
	v_cvt_f32_f16_sdwa v113, v80 dst_sel:DWORD dst_unused:UNUSED_PAD src0_sel:WORD_1
	v_cvt_f32_f16_e32 v80, v81
	v_cvt_f32_f16_sdwa v81, v81 dst_sel:DWORD dst_unused:UNUSED_PAD src0_sel:WORD_1
	ds_read_b128 v[92:95], v114 offset:39936
	s_waitcnt lgkmcnt(2)
	v_cvt_f32_f16_e32 v114, v88
	v_cvt_f32_f16_e32 v116, v89
	v_cvt_f32_f16_sdwa v117, v89 dst_sel:DWORD dst_unused:UNUSED_PAD src0_sel:WORD_1
	v_cvt_f32_f16_sdwa v115, v88 dst_sel:DWORD dst_unused:UNUSED_PAD src0_sel:WORD_1
	v_pk_mul_f32 v[88:89], v[50:51], v[72:73] op_sel_hi:[1,0]
	v_pk_fma_f32 v[116:117], v[118:119], v[80:81], v[116:117]
	v_pk_fma_f32 v[88:89], v[88:89], v[112:113], v[114:115]
	v_cvt_f32_f16_e32 v80, v82
	v_cvt_f32_f16_sdwa v81, v82 dst_sel:DWORD dst_unused:UNUSED_PAD src0_sel:WORD_1
	v_cvt_f32_f16_e32 v82, v83
	v_cvt_f32_f16_sdwa v83, v83 dst_sel:DWORD dst_unused:UNUSED_PAD src0_sel:WORD_1
	v_cvt_f32_f16_e32 v112, v90
	v_cvt_f32_f16_e32 v114, v91
	v_cvt_f32_f16_sdwa v115, v91 dst_sel:DWORD dst_unused:UNUSED_PAD src0_sel:WORD_1
	v_cvt_f32_f16_sdwa v113, v90 dst_sel:DWORD dst_unused:UNUSED_PAD src0_sel:WORD_1
	v_pk_mul_f32 v[90:91], v[54:55], v[72:73] op_sel_hi:[1,0]
	v_pk_mul_f32 v[118:119], v[56:57], v[72:73] op_sel_hi:[1,0]
	v_pk_fma_f32 v[90:91], v[90:91], v[80:81], v[112:113]
	v_pk_fma_f32 v[114:115], v[118:119], v[82:83], v[114:115]
	s_waitcnt lgkmcnt(1)
	v_cvt_f32_f16_e32 v80, v84
	v_cvt_f32_f16_sdwa v81, v84 dst_sel:DWORD dst_unused:UNUSED_PAD src0_sel:WORD_1
	v_cvt_f32_f16_e32 v82, v85
	v_cvt_f32_f16_sdwa v83, v85 dst_sel:DWORD dst_unused:UNUSED_PAD src0_sel:WORD_1
	s_waitcnt lgkmcnt(0)
	v_cvt_f32_f16_e32 v84, v92
	v_cvt_f32_f16_e32 v112, v93
	v_cvt_f32_f16_sdwa v113, v93 dst_sel:DWORD dst_unused:UNUSED_PAD src0_sel:WORD_1
	v_cvt_f32_f16_sdwa v85, v92 dst_sel:DWORD dst_unused:UNUSED_PAD src0_sel:WORD_1
	v_pk_mul_f32 v[92:93], v[58:59], v[72:73] op_sel_hi:[1,0]
	v_pk_mul_f32 v[118:119], v[60:61], v[72:73] op_sel_hi:[1,0]
	v_pk_fma_f32 v[84:85], v[92:93], v[80:81], v[84:85]
	v_pk_fma_f32 v[112:113], v[118:119], v[82:83], v[112:113]
	v_cvt_f32_f16_e32 v80, v86
	v_cvt_f32_f16_sdwa v81, v86 dst_sel:DWORD dst_unused:UNUSED_PAD src0_sel:WORD_1
	v_cvt_f32_f16_e32 v82, v87
	v_cvt_f32_f16_sdwa v83, v87 dst_sel:DWORD dst_unused:UNUSED_PAD src0_sel:WORD_1
	v_cvt_f32_f16_e32 v86, v94
	v_cvt_f32_f16_e32 v92, v95
	v_cvt_f32_f16_sdwa v93, v95 dst_sel:DWORD dst_unused:UNUSED_PAD src0_sel:WORD_1
	v_cvt_f32_f16_sdwa v87, v94 dst_sel:DWORD dst_unused:UNUSED_PAD src0_sel:WORD_1
	v_pk_mul_f32 v[94:95], v[62:63], v[72:73] op_sel_hi:[1,0]
	v_pk_mul_f32 v[118:119], v[64:65], v[72:73] op_sel_hi:[1,0]
	v_pk_fma_f32 v[86:87], v[94:95], v[80:81], v[86:87]
	v_pk_fma_f32 v[92:93], v[118:119], v[82:83], v[92:93]
	v_cvt_pk_bf16_f32 v80, v96, v97
	v_cvt_pk_bf16_f32 v81, v100, v101
	v_cvt_pk_bf16_f32 v82, v102, v103
	v_cvt_pk_bf16_f32 v83, v98, v99
	global_store_dwordx4 v[70:71], v[80:83], off nt
	s_nop 1
	v_cvt_pk_bf16_f32 v80, v106, v107
	v_cvt_pk_bf16_f32 v81, v104, v105
	v_cvt_pk_bf16_f32 v82, v110, v111
	v_cvt_pk_bf16_f32 v83, v108, v109
	global_store_dwordx4 v[70:71], v[80:83], off offset:1024 nt
	s_nop 1
	v_cvt_pk_bf16_f32 v80, v88, v89
	v_cvt_pk_bf16_f32 v81, v116, v117
	v_cvt_pk_bf16_f32 v82, v90, v91
	v_cvt_pk_bf16_f32 v83, v114, v115
	global_store_dwordx4 v[70:71], v[80:83], off offset:2048 nt
	s_nop 1
	v_cvt_pk_bf16_f32 v80, v84, v85
	v_cvt_pk_bf16_f32 v81, v112, v113
	v_cvt_pk_bf16_f32 v82, v86, v87
	v_cvt_pk_bf16_f32 v83, v92, v93
	global_store_dwordx4 v[70:71], v[80:83], off offset:3072 nt
	s_cbranch_scc1 .LBB0_1377
	s_lshl_b64 s[0:1], s[8:9], 12
	v_cvt_pk_f16_f32 v81, v36, v37
	v_cvt_pk_f16_f32 v80, v34, v35
	v_cvt_pk_f16_f32 v82, v38, v39
	v_lshl_add_u64 v[38:39], v[68:69], 0, s[0:1]
	v_cvt_pk_f16_f32 v35, v44, v45
	v_cvt_pk_f16_f32 v34, v42, v43
	v_cvt_pk_f16_f32 v37, v48, v49
	v_cvt_pk_f16_f32 v36, v46, v47
	global_store_dwordx4 v[38:39], v[34:37], off offset:1024 nt
	v_cvt_pk_f16_f32 v83, v40, v41
	global_store_dwordx4 v[38:39], v[80:83], off nt
	v_cvt_pk_f16_f32 v35, v52, v53
	v_cvt_pk_f16_f32 v34, v50, v51
	v_cvt_pk_f16_f32 v37, v56, v57
	v_cvt_pk_f16_f32 v36, v54, v55
	global_store_dwordx4 v[38:39], v[34:37], off offset:2048 nt
	s_nop 1
	v_cvt_pk_f16_f32 v35, v60, v61
	v_cvt_pk_f16_f32 v34, v58, v59
	v_cvt_pk_f16_f32 v37, v64, v65
	v_cvt_pk_f16_f32 v36, v62, v63
	global_store_dwordx4 v[38:39], v[34:37], off offset:3072 nt
	s_branch .LBB0_1377

; #define LAS __attribute__((address_space(3)))
; __device__ __forceinline__ f32x4 h4_to_f32x4(u32x2 v) { return __builtin_convertvector(__builtin_bit_cast(f16x4, v), f32x4); }
; template <bool COMBINE, bool SRC_F32>
; __device__ __forceinline__ void norm_phase(LAS unsigned char* lds, const void* src_lat, const void* src_ctx, _Float16* xw_ctx, const float* part, int nrows, const float* g, const float* modl, int shift_idx, int scale_idx, bf16* HN, int tid, int lane, int wave) {
;     ...
;     for (int row = gw; row < nrows; row += NGW) {
;         if (row + NGW < nrows) NORM_LOAD(nv, row + NGW);
;         const int r = row < M_LAT ? (row >> 11) : 8;
;         float ss = 0.f;
; #pragma unroll
;         for (int j = 0; j < 8; ++j) ss += (v[j][0] * v[j][0] + v[j][1] * v[j][1]) + (v[j][2] * v[j][2] + v[j][3] * v[j][3]);
;         const float rstd = 1.0f / sqrtf(wave_sum_dpp(ss) * (1.0f / D) + EPS);
;         bf16* o = HN + (size_t)row * D;
;         f32x4 y[8];
; #pragma unroll
;         for (int j = 0; j < 8; ++j) { const int c = NORM_COL(j); y[j] = (v[j] * rstd) * h4_to_f32x4(*(const LAS u32x2*)(Gs + r * D + c)) + h4_to_f32x4(*(const LAS u32x2*)(Ss + r * D + c)); }
.LBB0_2365:
	v_mul_f32_e32 v70, v35, v35
	v_mul_f32_e32 v74, v69, v69
	v_fmac_f32_e32 v70, v34, v34
	v_fmac_f32_e32 v74, v68, v68
	v_add_f32_e32 v70, v70, v74
	v_mul_f32_e32 v74, v63, v63
	v_mul_f32_e32 v75, v67, v67
	v_fmac_f32_e32 v74, v62, v62
	v_fmac_f32_e32 v75, v66, v66
	v_add_f32_e32 v74, v74, v75
	v_add_f32_e32 v70, v70, v74
	v_mul_f32_e32 v74, v61, v61
	v_mul_f32_e32 v75, v65, v65
	v_fmac_f32_e32 v74, v60, v60
	v_fmac_f32_e32 v75, v64, v64
	v_add_f32_e32 v74, v74, v75
	v_add_f32_e32 v70, v74, v70
	v_mul_f32_e32 v74, v59, v59
	v_mul_f32_e32 v75, v57, v57
	v_fmac_f32_e32 v74, v58, v58
	v_fmac_f32_e32 v75, v56, v56
	v_add_f32_e32 v74, v74, v75
	v_add_f32_e32 v70, v74, v70
	v_mul_f32_e32 v74, v49, v49
	v_mul_f32_e32 v75, v55, v55
	v_fmac_f32_e32 v74, v48, v48
	v_fmac_f32_e32 v75, v54, v54
	v_add_f32_e32 v74, v74, v75
	v_add_f32_e32 v70, v74, v70
	v_mul_f32_e32 v74, v47, v47
	v_mul_f32_e32 v75, v53, v53
	v_fmac_f32_e32 v74, v46, v46
	v_fmac_f32_e32 v75, v52, v52
	v_add_f32_e32 v74, v74, v75
	v_add_f32_e32 v70, v74, v70
	v_mul_f32_e32 v74, v45, v45
	v_mul_f32_e32 v75, v51, v51
	v_fmac_f32_e32 v74, v44, v44
	v_fmac_f32_e32 v75, v50, v50
	v_add_f32_e32 v74, v74, v75
	v_add_f32_e32 v70, v74, v70
	v_mul_f32_e32 v74, v41, v41
	v_mul_f32_e32 v75, v43, v43
	v_fmac_f32_e32 v74, v40, v40
	v_fmac_f32_e32 v75, v42, v42
	v_add_f32_e32 v74, v74, v75
	v_add_f32_e32 v70, v74, v70
	v_mov_b32_e32 v74, 0
	s_nop 0
	v_add_f32_dpp v70, v70, v70 quad_perm:[1,0,3,2] row_mask:0xf bank_mask:0xf bound_ctrl:1
	s_nop 1
	v_add_f32_dpp v70, v70, v70 quad_perm:[2,3,0,1] row_mask:0xf bank_mask:0xf bound_ctrl:1
	s_nop 1
	v_add_f32_dpp v70, v70, v70 row_half_mirror row_mask:0xf bank_mask:0xf bound_ctrl:1
	s_nop 1
	v_add_f32_dpp v70, v70, v70 row_mirror row_mask:0xf bank_mask:0xf bound_ctrl:1
	s_nop 1
	v_mov_b32_dpp v74, v70 row_bcast:15 row_mask:0xa bank_mask:0xf
	v_add_f32_e32 v70, v70, v74
	v_mov_b32_e32 v74, 0
	s_nop 1
	v_mov_b32_dpp v74, v70 row_bcast:31 row_mask:0xc bank_mask:0xf
	v_add_f32_e32 v70, v70, v74
	s_nop 0
	v_readlane_b32 s0, v70, 63
	s_nop 1
	v_fma_f32 v70, s0, v73, v71
	v_mul_f32_e32 v74, 0x4f800000, v70
	v_cmp_gt_f32_e32 vcc, s5, v70
	s_nop 1
	v_cndmask_b32_e32 v70, v70, v74, vcc
	v_sqrt_f32_e32 v74, v70
	s_nop 0
	v_add_u32_e32 v75, -1, v74
	v_fma_f32 v76, -v75, v74, v70
	v_cmp_ge_f32_e64 s[0:1], 0, v76
	v_add_u32_e32 v76, 1, v74
	s_nop 0
	v_cndmask_b32_e64 v75, v74, v75, s[0:1]
	v_fma_f32 v74, -v76, v74, v70
	v_cmp_lt_f32_e64 s[0:1], 0, v74
	s_nop 1
	v_cndmask_b32_e64 v74, v75, v76, s[0:1]
	v_mul_f32_e32 v75, 0x37800000, v74
	v_cndmask_b32_e32 v74, v74, v75, vcc
	v_cmp_class_f32_e32 vcc, v70, v72
	s_nop 1
	v_cndmask_b32_e32 v70, v74, v70, vcc
	v_div_scale_f32 v74, s[0:1], v70, v70, 1.0
	v_rcp_f32_e32 v78, v74
	s_and_b32 s0, s8, 0x7ffff800
	v_lshl_add_u32 v96, s0, 1, v1
	ds_read_b128 v[82:85], v96 offset:36864
	ds_read_b128 v[86:89], v96 offset:37888
	v_fma_f32 v75, -v74, v78, 1.0
	v_fmac_f32_e32 v78, v75, v78
	v_div_scale_f32 v75, vcc, 1.0, v70, 1.0
	v_mul_f32_e32 v79, v75, v78
	v_fma_f32 v76, -v74, v79, v75
	v_fmac_f32_e32 v79, v76, v78
	v_fma_f32 v80, -v74, v79, v75
	ds_read_b128 v[74:77], v96
	v_div_fmas_f32 v78, v80, v78, v79
	v_div_fixup_f32 v70, v78, v70, 1.0
	ds_read_b128 v[78:81], v96 offset:1024
	s_waitcnt lgkmcnt(3)
	v_cvt_f32_f16_e32 v92, v82
	s_waitcnt lgkmcnt(1)
	v_cvt_f32_f16_e32 v90, v74
	v_cvt_f32_f16_sdwa v91, v74 dst_sel:DWORD dst_unused:UNUSED_PAD src0_sel:WORD_1
	v_cvt_f32_f16_e32 v74, v75
	v_cvt_f32_f16_sdwa v75, v75 dst_sel:DWORD dst_unused:UNUSED_PAD src0_sel:WORD_1
	v_cvt_f32_f16_e32 v94, v83
	v_cvt_f32_f16_sdwa v95, v83 dst_sel:DWORD dst_unused:UNUSED_PAD src0_sel:WORD_1
	v_cvt_f32_f16_sdwa v93, v82 dst_sel:DWORD dst_unused:UNUSED_PAD src0_sel:WORD_1
	v_pk_mul_f32 v[34:35], v[34:35], v[70:71] op_sel_hi:[1,0]
	v_pk_mul_f32 v[68:69], v[68:69], v[70:71] op_sel_hi:[1,0]
	v_cvt_f32_f16_e32 v82, v84
	v_pk_fma_f32 v[74:75], v[68:69], v[74:75], v[94:95]
	v_pk_fma_f32 v[34:35], v[34:35], v[90:91], v[92:93]
	v_cvt_f32_f16_e32 v68, v76
	v_cvt_f32_f16_sdwa v69, v76 dst_sel:DWORD dst_unused:UNUSED_PAD src0_sel:WORD_1
	v_cvt_f32_f16_e32 v76, v77
	v_cvt_f32_f16_sdwa v77, v77 dst_sel:DWORD dst_unused:UNUSED_PAD src0_sel:WORD_1
	v_cvt_f32_f16_e32 v90, v85
	v_cvt_f32_f16_sdwa v91, v85 dst_sel:DWORD dst_unused:UNUSED_PAD src0_sel:WORD_1
	v_cvt_f32_f16_sdwa v83, v84 dst_sel:DWORD dst_unused:UNUSED_PAD src0_sel:WORD_1
	v_pk_mul_f32 v[62:63], v[62:63], v[70:71] op_sel_hi:[1,0]
	v_pk_mul_f32 v[66:67], v[66:67], v[70:71] op_sel_hi:[1,0]
	v_pk_mul_f32 v[60:61], v[60:61], v[70:71] op_sel_hi:[1,0]
	v_pk_fma_f32 v[76:77], v[66:67], v[76:77], v[90:91]
	v_pk_fma_f32 v[82:83], v[62:63], v[68:69], v[82:83]
	s_waitcnt lgkmcnt(0)
; __device__ __forceinline__ unsigned cvt_pk_bf16(float lo, float hi) { unsigned r; asm volatile("v_cvt_pk_bf16_f32 %0, %1, %2" : "=v"(r) : "v"(lo), "v"(hi)); return r; }
; #define LAS __attribute__((address_space(3)))
; __device__ __forceinline__ u32x2 f32x4_to_h4(f32x4 v) { return __builtin_bit_cast(u32x2, __builtin_convertvector(v, f16x4)); }
; __device__ __forceinline__ f32x4 h4_to_f32x4(u32x2 v) { return __builtin_convertvector(__builtin_bit_cast(f16x4, v), f32x4); }
; template <bool COMBINE, bool SRC_F32>
; __device__ __forceinline__ void norm_phase(LAS unsigned char* lds, const void* src_lat, const void* src_ctx, _Float16* xw_ctx, const float* part, int nrows, const float* g, const float* modl, int shift_idx, int scale_idx, bf16* HN, int tid, int lane, int wave) {
;     ...
;         for (int j = 0; j < 8; ++j) { const int c = NORM_COL(j); y[j] = (v[j] * rstd) * h4_to_f32x4(*(const LAS u32x2*)(Gs + r * D + c)) + h4_to_f32x4(*(const LAS u32x2*)(Ss + r * D + c)); }
;         if constexpr (SRC_F32) {
; #pragma unroll
;             for (int j = 0; j < 8; ++j) { u32x2 w; w.x = pg8::cvt_pk_bf16(y[j][0], y[j][1]); w.y = pg8::cvt_pk_bf16(y[j][2], y[j][3]); *(u32x2*)(o + NORM_COL(j)) = w; }
;         } else {
; #pragma unroll
;             for (int j = 0; j < 4; ++j) { u32x4 w; w.x = pg8::cvt_pk_bf16(y[2 * j][0], y[2 * j][1]); w.y = pg8::cvt_pk_bf16(y[2 * j][2], y[2 * j][3]); w.z = pg8::cvt_pk_bf16(y[2 * j + 1][0], y[2 * j + 1][1]); w.w = pg8::cvt_pk_bf16(y[2 * j + 1][2], y[2 * j + 1][3]);
;                 *(u32x4*)(o + NORM_COL(2 * j)) = w; }
;         }
;         if (COMBINE && row >= M_LAT) {
; #pragma unroll
;             for (int j = 0; j < 4; ++j) { const u32x2 h0 = f32x4_to_h4(v[2 * j]), h1 = f32x4_to_h4(v[2 * j + 1]); *(u32x4*)(xw_ctx + (size_t)(row - M_LAT) * D + NORM_COL(2 * j)) = (u32x4){h0.x, h0.y, h1.x, h1.y}; }
;         }
; #pragma unroll
;         for (int j = 0; j < 8; ++j) v[j] = nv[j];
	v_cvt_f32_f16_e32 v62, v78
	v_cvt_f32_f16_sdwa v63, v78 dst_sel:DWORD dst_unused:UNUSED_PAD src0_sel:WORD_1
	v_cvt_f32_f16_e32 v66, v79
	v_cvt_f32_f16_sdwa v67, v79 dst_sel:DWORD dst_unused:UNUSED_PAD src0_sel:WORD_1
	v_cvt_f32_f16_e32 v68, v86
	v_cvt_f32_f16_e32 v78, v87
	v_cvt_f32_f16_sdwa v79, v87 dst_sel:DWORD dst_unused:UNUSED_PAD src0_sel:WORD_1
	v_cvt_f32_f16_sdwa v69, v86 dst_sel:DWORD dst_unused:UNUSED_PAD src0_sel:WORD_1
	v_pk_mul_f32 v[64:65], v[64:65], v[70:71] op_sel_hi:[1,0]
	v_pk_mul_f32 v[56:57], v[56:57], v[70:71] op_sel_hi:[1,0]
	v_pk_fma_f32 v[78:79], v[64:65], v[66:67], v[78:79]
	v_pk_fma_f32 v[84:85], v[60:61], v[62:63], v[68:69]
	v_cvt_f32_f16_e32 v64, v80
	v_cvt_f32_f16_sdwa v65, v80 dst_sel:DWORD dst_unused:UNUSED_PAD src0_sel:WORD_1
	v_cvt_f32_f16_e32 v66, v81
	v_cvt_f32_f16_sdwa v67, v81 dst_sel:DWORD dst_unused:UNUSED_PAD src0_sel:WORD_1
	v_cvt_f32_f16_e32 v68, v88
	v_cvt_f32_f16_e32 v80, v89
	v_cvt_f32_f16_sdwa v81, v89 dst_sel:DWORD dst_unused:UNUSED_PAD src0_sel:WORD_1
	v_cvt_f32_f16_sdwa v69, v88 dst_sel:DWORD dst_unused:UNUSED_PAD src0_sel:WORD_1
	v_pk_mul_f32 v[62:63], v[58:59], v[70:71] op_sel_hi:[1,0]
	ds_read_b128 v[58:61], v96 offset:2048
	v_pk_fma_f32 v[80:81], v[56:57], v[66:67], v[80:81]
	v_pk_fma_f32 v[86:87], v[62:63], v[64:65], v[68:69]
	ds_read_b128 v[66:69], v96 offset:38912
	ds_read_b128 v[62:65], v96 offset:3072
	s_waitcnt lgkmcnt(2)
	v_cvt_f32_f16_e32 v88, v58
	v_cvt_f32_f16_sdwa v89, v58 dst_sel:DWORD dst_unused:UNUSED_PAD src0_sel:WORD_1
	v_cvt_f32_f16_e32 v90, v59
	v_cvt_f32_f16_sdwa v91, v59 dst_sel:DWORD dst_unused:UNUSED_PAD src0_sel:WORD_1
	ds_read_b128 v[56:59], v96 offset:39936
	s_waitcnt lgkmcnt(2)
	v_cvt_f32_f16_e32 v92, v66
	v_cvt_f32_f16_e32 v94, v67
	v_cvt_f32_f16_sdwa v95, v67 dst_sel:DWORD dst_unused:UNUSED_PAD src0_sel:WORD_1
	v_cvt_f32_f16_sdwa v93, v66 dst_sel:DWORD dst_unused:UNUSED_PAD src0_sel:WORD_1
	v_pk_mul_f32 v[48:49], v[48:49], v[70:71] op_sel_hi:[1,0]
	v_pk_mul_f32 v[54:55], v[54:55], v[70:71] op_sel_hi:[1,0]
	v_cvt_f32_f16_e32 v66, v60
	v_pk_fma_f32 v[54:55], v[54:55], v[90:91], v[94:95]
	v_pk_fma_f32 v[48:49], v[48:49], v[88:89], v[92:93]
	v_cvt_f32_f16_sdwa v67, v60 dst_sel:DWORD dst_unused:UNUSED_PAD src0_sel:WORD_1
	v_cvt_f32_f16_e32 v60, v61
	v_cvt_f32_f16_sdwa v61, v61 dst_sel:DWORD dst_unused:UNUSED_PAD src0_sel:WORD_1
	v_cvt_f32_f16_e32 v88, v68
	v_cvt_f32_f16_e32 v90, v69
	v_cvt_f32_f16_sdwa v91, v69 dst_sel:DWORD dst_unused:UNUSED_PAD src0_sel:WORD_1
	v_cvt_f32_f16_sdwa v89, v68 dst_sel:DWORD dst_unused:UNUSED_PAD src0_sel:WORD_1
	v_pk_mul_f32 v[46:47], v[46:47], v[70:71] op_sel_hi:[1,0]
	v_pk_mul_f32 v[52:53], v[52:53], v[70:71] op_sel_hi:[1,0]
	s_waitcnt lgkmcnt(0)
	v_cvt_f32_f16_e32 v68, v57
	v_pk_fma_f32 v[52:53], v[52:53], v[60:61], v[90:91]
	v_pk_fma_f32 v[46:47], v[46:47], v[66:67], v[88:89]
	v_cvt_f32_f16_e32 v60, v62
	v_cvt_f32_f16_sdwa v61, v62 dst_sel:DWORD dst_unused:UNUSED_PAD src0_sel:WORD_1
	v_cvt_f32_f16_e32 v62, v63
	v_cvt_f32_f16_sdwa v63, v63 dst_sel:DWORD dst_unused:UNUSED_PAD src0_sel:WORD_1
	v_cvt_f32_f16_e32 v66, v56
	v_cvt_f32_f16_sdwa v69, v57 dst_sel:DWORD dst_unused:UNUSED_PAD src0_sel:WORD_1
	v_cvt_f32_f16_sdwa v67, v56 dst_sel:DWORD dst_unused:UNUSED_PAD src0_sel:WORD_1
	v_pk_mul_f32 v[44:45], v[44:45], v[70:71] op_sel_hi:[1,0]
	v_pk_mul_f32 v[50:51], v[50:51], v[70:71] op_sel_hi:[1,0]
	v_cvt_f32_f16_e32 v56, v64
	v_pk_fma_f32 v[50:51], v[50:51], v[62:63], v[68:69]
	v_pk_fma_f32 v[44:45], v[44:45], v[60:61], v[66:67]
	v_cvt_f32_f16_sdwa v57, v64 dst_sel:DWORD dst_unused:UNUSED_PAD src0_sel:WORD_1
	v_cvt_f32_f16_e32 v60, v65
	v_cvt_f32_f16_sdwa v61, v65 dst_sel:DWORD dst_unused:UNUSED_PAD src0_sel:WORD_1
	v_cvt_f32_f16_e32 v62, v58
	v_cvt_f32_f16_e32 v64, v59
	v_cvt_f32_f16_sdwa v65, v59 dst_sel:DWORD dst_unused:UNUSED_PAD src0_sel:WORD_1
	v_cvt_f32_f16_sdwa v63, v58 dst_sel:DWORD dst_unused:UNUSED_PAD src0_sel:WORD_1
	v_pk_mul_f32 v[40:41], v[40:41], v[70:71] op_sel_hi:[1,0]
	v_pk_mul_f32 v[42:43], v[42:43], v[70:71] op_sel_hi:[1,0]
	s_andn2_b64 vcc, exec, s[12:13]
	v_pk_fma_f32 v[58:59], v[42:43], v[60:61], v[64:65]
	v_pk_fma_f32 v[56:57], v[40:41], v[56:57], v[62:63]
	v_cvt_pk_bf16_f32 v40, v34, v35
	v_cvt_pk_bf16_f32 v41, v74, v75
	v_cvt_pk_bf16_f32 v42, v82, v83
	v_cvt_pk_bf16_f32 v43, v76, v77
	global_store_dwordx4 v[38:39], v[40:43], off nt
	s_mov_b32 s8, s10
	v_mov_b32_e32 v34, v2
	v_cvt_pk_bf16_f32 v40, v84, v85
	v_cvt_pk_bf16_f32 v41, v78, v79
	v_cvt_pk_bf16_f32 v42, v86, v87
	v_cvt_pk_bf16_f32 v43, v80, v81
	global_store_dwordx4 v[38:39], v[40:43], off offset:1024 nt
	v_mov_b32_e32 v35, v3
	v_mov_b32_e32 v68, v4
	v_cvt_pk_bf16_f32 v40, v48, v49
	v_cvt_pk_bf16_f32 v41, v54, v55
	v_cvt_pk_bf16_f32 v42, v46, v47
	v_cvt_pk_bf16_f32 v43, v52, v53
	global_store_dwordx4 v[38:39], v[40:43], off offset:2048 nt
	v_mov_b32_e32 v69, v5
	v_mov_b32_e32 v62, v6
	v_cvt_pk_bf16_f32 v40, v44, v45
	v_cvt_pk_bf16_f32 v41, v50, v51
	v_cvt_pk_bf16_f32 v42, v56, v57
	v_cvt_pk_bf16_f32 v43, v58, v59
	global_store_dwordx4 v[38:39], v[40:43], off offset:3072 nt
	v_lshl_add_u64 v[38:39], v[38:39], 0, s[6:7]
	v_mov_b32_e32 v63, v7
	v_mov_b32_e32 v66, v8
	v_mov_b32_e32 v67, v9
	v_mov_b32_e32 v60, v10
	v_mov_b32_e32 v61, v11
	v_mov_b32_e32 v64, v12
	v_mov_b32_e32 v65, v13
	v_mov_b32_e32 v58, v14
	v_mov_b32_e32 v59, v15
	v_mov_b32_e32 v56, v16
	v_mov_b32_e32 v57, v17
	v_mov_b32_e32 v48, v18
	v_mov_b32_e32 v49, v19
	v_mov_b32_e32 v54, v20
	v_mov_b32_e32 v55, v21
	v_mov_b32_e32 v46, v22
	v_mov_b32_e32 v47, v23
	v_mov_b32_e32 v52, v24
	v_mov_b32_e32 v53, v25
	v_mov_b32_e32 v44, v26
	v_mov_b32_e32 v45, v27
	v_mov_b32_e32 v50, v28
	v_mov_b32_e32 v51, v29
	v_mov_b32_e32 v40, v30
	v_mov_b32_e32 v41, v31
	v_mov_b32_e32 v42, v32
	v_mov_b32_e32 v43, v33
	s_cbranch_vccz .LBB0_2368
